# ah1 + nt (streaming) hint on the once-read row loads of modulate0 / rowpass1 / rowpass2 loops (80 loads)
# speedup vs baseline: 1.0079x; 1.0079x over previous
.LBB0_202:
	v_lshlrev_b32_e32 v84, 2, v64
	global_load_dwordx4 v[60:63], v84, s[4:5] nt
	global_load_dwordx4 v[56:59], v84, s[4:5] offset:1024 nt
	global_load_dwordx4 v[52:55], v84, s[4:5] offset:2048 nt
	global_load_dwordx4 v[48:51], v84, s[4:5] offset:3072 nt
	global_load_dwordx4 v[44:47], v78, s[4:5] nt
	global_load_dwordx4 v[40:43], v79, s[4:5] nt
	global_load_dwordx4 v[36:39], v80, s[4:5] nt
	global_load_dwordx4 v[32:35], v81, s[4:5] nt
	s_lshl_b64 s[22:23], s[22:23], 12
	v_lshl_add_u64 v[86:87], v[66:67], 0, s[22:23]
	s_add_i32 s22, s88, s20
	s_cmpk_lt_i32 s22, 0x4400
	s_cselect_b64 s[24:25], -1, 0
	s_cmpk_gt_i32 s22, 0x43ff
	s_cbranch_scc1 .Lmod0_one
	s_cmpk_lt_i32 s22, 0x4000
	s_mov_b64 s[26:27], -1
	s_cbranch_scc1 .LBB0_205
	s_load_dwordx2 s[4:5], s[6:7], 0x10
	s_add_i32 s8, s22, 0xffffc000
	s_lshl_b64 s[26:27], s[8:9], 13
	s_mov_b32 s23, s9
	s_waitcnt lgkmcnt(0)
	s_add_u32 s4, s4, s26
	s_addc_u32 s5, s5, s27
	s_mov_b64 s[26:27], 0

.LBB0_207:
	global_load_dwordx4 v[0:3], v84, s[4:5] nt
	global_load_dwordx4 v[4:7], v84, s[4:5] offset:1024 nt
	global_load_dwordx4 v[8:11], v84, s[4:5] offset:2048 nt
	global_load_dwordx4 v[12:15], v84, s[4:5] offset:3072 nt
	global_load_dwordx4 v[16:19], v78, s[4:5] nt
	global_load_dwordx4 v[20:23], v79, s[4:5] nt
	global_load_dwordx4 v[24:27], v80, s[4:5] nt
	global_load_dwordx4 v[28:31], v81, s[4:5] nt
	s_lshl_b64 s[26:27], s[22:23], 12
	v_lshl_add_u64 v[104:105], v[66:67], 0, s[26:27]
	s_waitcnt vmcnt(15)
	v_cvt_pk_f16_f32 v89, v62, v63
	v_cvt_pk_f16_f32 v88, v60, v61
	global_store_dwordx2 v[86:87], v[88:89], off
	s_waitcnt vmcnt(15)
	v_cvt_pk_f16_f32 v107, v58, v59
	v_cvt_pk_f16_f32 v106, v56, v57
	global_store_dwordx2 v[86:87], v[106:107], off offset:512
	s_waitcnt vmcnt(15)
	v_cvt_pk_f16_f32 v89, v54, v55
	v_cvt_pk_f16_f32 v88, v52, v53
	global_store_dwordx2 v[86:87], v[88:89], off offset:1024
	s_waitcnt vmcnt(15)
	v_cvt_pk_f16_f32 v107, v50, v51
	v_cvt_pk_f16_f32 v106, v48, v49
	global_store_dwordx2 v[86:87], v[106:107], off offset:1536
	s_waitcnt vmcnt(15)
	v_cvt_pk_f16_f32 v89, v46, v47
	v_cvt_pk_f16_f32 v88, v44, v45
	global_store_dwordx2 v[86:87], v[88:89], off offset:2048
	s_waitcnt vmcnt(15)
	v_cvt_pk_f16_f32 v107, v42, v43
	v_cvt_pk_f16_f32 v106, v40, v41
	global_store_dwordx2 v[86:87], v[106:107], off offset:2560
	s_waitcnt vmcnt(15)
	v_cvt_pk_f16_f32 v89, v38, v39
	v_cvt_pk_f16_f32 v88, v36, v37
	global_store_dwordx2 v[86:87], v[88:89], off offset:3072
	s_waitcnt vmcnt(15)
	v_cvt_pk_f16_f32 v107, v34, v35
	v_cvt_pk_f16_f32 v106, v32, v33
	global_store_dwordx2 v[86:87], v[106:107], off offset:3584
	s_waitcnt vmcnt(15)
	v_cvt_pk_f16_f32 v89, v2, v3
	v_cvt_pk_f16_f32 v88, v0, v1
	global_store_dwordx2 v[104:105], v[88:89], off
	s_waitcnt vmcnt(15)
	v_cvt_pk_f16_f32 v107, v6, v7
	v_cvt_pk_f16_f32 v106, v4, v5
	global_store_dwordx2 v[104:105], v[106:107], off offset:512
	s_waitcnt vmcnt(15)
	v_cvt_pk_f16_f32 v89, v10, v11
	v_cvt_pk_f16_f32 v88, v8, v9
	global_store_dwordx2 v[104:105], v[88:89], off offset:1024
	s_waitcnt vmcnt(15)
	v_cvt_pk_f16_f32 v107, v14, v15
	v_cvt_pk_f16_f32 v106, v12, v13
	global_store_dwordx2 v[104:105], v[106:107], off offset:1536
	s_waitcnt vmcnt(15)
	v_cvt_pk_f16_f32 v89, v18, v19
	v_cvt_pk_f16_f32 v88, v16, v17
	global_store_dwordx2 v[104:105], v[88:89], off offset:2048
	s_waitcnt vmcnt(15)
	v_cvt_pk_f16_f32 v107, v22, v23
	v_cvt_pk_f16_f32 v106, v20, v21
	global_store_dwordx2 v[104:105], v[106:107], off offset:2560
	s_waitcnt vmcnt(15)
	v_cvt_pk_f16_f32 v89, v26, v27
	v_cvt_pk_f16_f32 v88, v24, v25
	global_store_dwordx2 v[104:105], v[88:89], off offset:3072
	s_waitcnt vmcnt(15)
	v_cvt_pk_f16_f32 v107, v30, v31
	v_cvt_pk_f16_f32 v106, v28, v29
	global_store_dwordx2 v[104:105], v[106:107], off offset:3584
	s_branch .LBB0_208

.LBB0_919:
	v_add_co_u32_e32 v96, vcc, 0x4400000, v134
	s_lshr_b32 s6, s18, 12
	s_nop 0
	v_addc_co_u32_e32 v97, vcc, 0, v135, vcc
	v_add_co_u32_e32 v98, vcc, 0xf7800000, v134
	s_mulk_i32 s6, 0x6000
	s_nop 0
	v_addc_co_u32_e32 v99, vcc, -1, v135, vcc
	global_load_dwordx2 v[166:167], v[98:99], off nt
	v_add_co_u32_e32 v98, vcc, 0xf7801000, v134
	v_add_u32_e32 v144, s6, v176
	s_nop 0
	v_addc_co_u32_e32 v99, vcc, -1, v135, vcc
	global_load_dwordx2 v[168:169], v[96:97], off nt
	global_load_dwordx2 v[162:163], v[96:97], off offset:512 nt
	global_load_dwordx2 v[158:159], v[96:97], off offset:1024 nt
	global_load_dwordx2 v[156:157], v[96:97], off offset:1536 nt
	global_load_dwordx2 v[164:165], v[98:99], off offset:-3584 nt
	global_load_dwordx2 v[160:161], v[98:99], off offset:-3072 nt
	global_load_dwordx2 v[154:155], v[98:99], off offset:-2560 nt
	global_load_dwordx2 v[150:151], v[98:99], off offset:-2048 nt
	global_load_dwordx2 v[152:153], v[96:97], off offset:2048 nt
	global_load_dwordx2 v[146:147], v[96:97], off offset:2560 nt
	global_load_dwordx2 v[140:141], v[96:97], off offset:3072 nt
	global_load_dwordx2 v[138:139], v[96:97], off offset:3584 nt
	global_load_dwordx2 v[148:149], v[98:99], off offset:-1536 nt
	global_load_dwordx2 v[142:143], v[98:99], off offset:-1024 nt
	global_load_dwordx2 v[136:137], v[98:99], off offset:-512 nt
	ds_read_b128 v[124:127], v144 offset:16384
	ds_read_b128 v[120:123], v144 offset:17408
	ds_read_b128 v[116:119], v144 offset:18432
	ds_read_b128 v[112:115], v144 offset:19456
	ds_read_b128 v[108:111], v144 offset:20480
	ds_read_b128 v[104:107], v144 offset:21504
	ds_read_b128 v[100:103], v144 offset:22528
	ds_read_b128 v[96:99], v144 offset:23552
	s_add_i32 s14, s88, s18
	s_cmpk_lt_i32 s14, 0x4000
	s_cselect_b64 s[16:17], -1, 0
	s_cmpk_gt_i32 s14, 0x3fff
	s_cbranch_scc1 .LBB0_921
	s_ashr_i32 s15, s14, 31
	s_lshl_b64 s[6:7], s[14:15], 12
	v_lshl_add_u64 v[88:89], v[128:129], 0, s[6:7]
	global_load_dwordx2 v[90:91], v[88:89], off nt
	v_lshl_add_u64 v[92:93], v[130:131], 0, s[6:7]
	s_lshr_b32 s6, s14, 12
	global_load_dwordx2 v[94:95], v[92:93], off nt
	global_load_dwordx2 v[178:179], v[88:89], off offset:512 nt
	global_load_dwordx2 v[180:181], v[92:93], off offset:512 nt
	global_load_dwordx2 v[182:183], v[88:89], off offset:1024 nt
	global_load_dwordx2 v[184:185], v[92:93], off offset:1024 nt
	global_load_dwordx2 v[186:187], v[88:89], off offset:1536 nt
	global_load_dwordx2 v[188:189], v[92:93], off offset:1536 nt
	global_load_dwordx2 v[190:191], v[88:89], off offset:2048 nt
	global_load_dwordx2 v[192:193], v[92:93], off offset:2048 nt
	global_load_dwordx2 v[194:195], v[88:89], off offset:2560 nt
	global_load_dwordx2 v[196:197], v[92:93], off offset:2560 nt
	s_mulk_i32 s6, 0x6000
	v_add_u32_e32 v177, s6, v176
	ds_read_b128 v[64:67], v177 offset:16384
	ds_read_b128 v[68:71], v177 offset:17408
	global_load_dwordx2 v[198:199], v[88:89], off offset:3072 nt
	ds_read_b128 v[72:75], v177 offset:18432
	ds_read_b128 v[76:79], v177 offset:19456
	global_load_dwordx2 v[200:201], v[92:93], off offset:3072 nt
	ds_read_b128 v[80:83], v177 offset:20480
	ds_read_b128 v[84:87], v177 offset:21504
	global_load_dwordx2 v[202:203], v[88:89], off offset:3584 nt
	global_load_dwordx2 v[204:205], v[92:93], off offset:3584 nt
	s_waitcnt vmcnt(14)
	v_cvt_f32_f16_e32 v92, v94
	v_cvt_f32_f16_sdwa v93, v94 dst_sel:DWORD dst_unused:UNUSED_PAD src0_sel:WORD_1
	v_cvt_f32_f16_e32 v94, v95
	v_cvt_f32_f16_sdwa v95, v95 dst_sel:DWORD dst_unused:UNUSED_PAD src0_sel:WORD_1
	s_waitcnt vmcnt(10)
	v_cvt_f32_f16_e32 v212, v184
	v_cvt_f32_f16_sdwa v213, v184 dst_sel:DWORD dst_unused:UNUSED_PAD src0_sel:WORD_1
	v_cvt_f32_f16_e32 v184, v185
	v_lshlrev_b32_e32 v88, 16, v90
	v_and_b32_e32 v89, 0xffff0000, v90
	v_lshlrev_b32_e32 v90, 16, v91
	v_and_b32_e32 v91, 0xffff0000, v91
	v_cvt_f32_f16_sdwa v185, v185 dst_sel:DWORD dst_unused:UNUSED_PAD src0_sel:WORD_1
	s_waitcnt lgkmcnt(5)
	v_pk_mul_f32 v[66:67], v[66:67], v[90:91]
	v_pk_mul_f32 v[64:65], v[64:65], v[88:89]
	s_waitcnt vmcnt(5)
	v_lshlrev_b32_e32 v88, 16, v194
	v_and_b32_e32 v89, 0xffff0000, v194
	v_lshlrev_b32_e32 v90, 16, v195
	v_and_b32_e32 v91, 0xffff0000, v195
	v_cvt_f32_f16_e32 v208, v180
	v_cvt_f32_f16_sdwa v209, v180 dst_sel:DWORD dst_unused:UNUSED_PAD src0_sel:WORD_1
	v_cvt_f32_f16_e32 v180, v181
	v_cvt_f32_f16_sdwa v181, v181 dst_sel:DWORD dst_unused:UNUSED_PAD src0_sel:WORD_1
	v_lshlrev_b32_e32 v210, 16, v182
	v_and_b32_e32 v211, 0xffff0000, v182
	v_lshlrev_b32_e32 v182, 16, v183
	v_and_b32_e32 v183, 0xffff0000, v183
	v_pk_fma_f32 v[66:67], v[94:95], s[30:31], v[66:67] op_sel_hi:[1,0,1]
	v_pk_fma_f32 v[64:65], v[92:93], s[30:31], v[64:65] op_sel_hi:[1,0,1]
	s_waitcnt vmcnt(4)
	v_cvt_f32_f16_e32 v92, v196
	v_cvt_f32_f16_e32 v94, v197
	v_cvt_f32_f16_sdwa v95, v197 dst_sel:DWORD dst_unused:UNUSED_PAD src0_sel:WORD_1
	v_cvt_f32_f16_sdwa v93, v196 dst_sel:DWORD dst_unused:UNUSED_PAD src0_sel:WORD_1
	s_waitcnt lgkmcnt(0)
	v_pk_mul_f32 v[86:87], v[86:87], v[90:91]
	v_pk_mul_f32 v[84:85], v[84:85], v[88:89]
	ds_read_b128 v[88:91], v177 offset:22528
	v_pk_mul_f32 v[74:75], v[74:75], v[182:183]
	v_lshlrev_b32_e32 v206, 16, v178
	v_and_b32_e32 v207, 0xffff0000, v178
	v_lshlrev_b32_e32 v178, 16, v179
	v_and_b32_e32 v179, 0xffff0000, v179
	v_pk_fma_f32 v[74:75], v[184:185], s[30:31], v[74:75] op_sel_hi:[1,0,1]
	s_waitcnt vmcnt(2)
	v_cvt_f32_f16_e32 v182, v200
	v_cvt_f32_f16_sdwa v183, v200 dst_sel:DWORD dst_unused:UNUSED_PAD src0_sel:WORD_1
	v_cvt_f32_f16_e32 v184, v201
	v_cvt_f32_f16_sdwa v185, v201 dst_sel:DWORD dst_unused:UNUSED_PAD src0_sel:WORD_1
	v_pk_mul_f32 v[70:71], v[70:71], v[178:179]
	v_pk_fma_f32 v[86:87], v[94:95], s[30:31], v[86:87] op_sel_hi:[1,0,1]
	v_pk_fma_f32 v[70:71], v[180:181], s[30:31], v[70:71] op_sel_hi:[1,0,1]
	v_pk_fma_f32 v[84:85], v[92:93], s[30:31], v[84:85] op_sel_hi:[1,0,1]
	v_lshlrev_b32_e32 v178, 16, v198
	v_and_b32_e32 v179, 0xffff0000, v198
	v_lshlrev_b32_e32 v180, 16, v199
	v_and_b32_e32 v181, 0xffff0000, v199
	ds_read_b128 v[92:95], v177 offset:23552
	s_waitcnt lgkmcnt(1)
	v_pk_mul_f32 v[90:91], v[90:91], v[180:181]
	v_pk_mul_f32 v[88:89], v[88:89], v[178:179]
	v_cvt_f32_f16_e32 v216, v188
	v_cvt_f32_f16_sdwa v217, v188 dst_sel:DWORD dst_unused:UNUSED_PAD src0_sel:WORD_1
	v_cvt_f32_f16_e32 v188, v189
	v_cvt_f32_f16_sdwa v189, v189 dst_sel:DWORD dst_unused:UNUSED_PAD src0_sel:WORD_1
	v_cvt_f32_f16_e32 v220, v192
	v_cvt_f32_f16_sdwa v221, v192 dst_sel:DWORD dst_unused:UNUSED_PAD src0_sel:WORD_1
	v_cvt_f32_f16_e32 v192, v193
	v_cvt_f32_f16_sdwa v193, v193 dst_sel:DWORD dst_unused:UNUSED_PAD src0_sel:WORD_1
	v_pk_fma_f32 v[90:91], v[184:185], s[30:31], v[90:91] op_sel_hi:[1,0,1]
	v_pk_fma_f32 v[88:89], v[182:183], s[30:31], v[88:89] op_sel_hi:[1,0,1]
	s_waitcnt vmcnt(0)
	v_cvt_f32_f16_e32 v182, v204
	v_cvt_f32_f16_e32 v184, v205
	v_cvt_f32_f16_sdwa v185, v205 dst_sel:DWORD dst_unused:UNUSED_PAD src0_sel:WORD_1
	v_cvt_f32_f16_sdwa v183, v204 dst_sel:DWORD dst_unused:UNUSED_PAD src0_sel:WORD_1
	v_lshlrev_b32_e32 v214, 16, v186
	v_and_b32_e32 v215, 0xffff0000, v186
	v_lshlrev_b32_e32 v186, 16, v187
	v_and_b32_e32 v187, 0xffff0000, v187
	v_lshlrev_b32_e32 v218, 16, v190
	v_and_b32_e32 v219, 0xffff0000, v190
	v_lshlrev_b32_e32 v190, 16, v191
	v_and_b32_e32 v191, 0xffff0000, v191
	v_lshlrev_b32_e32 v178, 16, v202
	v_and_b32_e32 v179, 0xffff0000, v202
	v_lshlrev_b32_e32 v180, 16, v203
	v_and_b32_e32 v181, 0xffff0000, v203
	v_pk_mul_f32 v[68:69], v[68:69], v[206:207]
	v_pk_mul_f32 v[72:73], v[72:73], v[210:211]
	v_pk_mul_f32 v[78:79], v[78:79], v[186:187]
	v_pk_mul_f32 v[76:77], v[76:77], v[214:215]
	v_pk_mul_f32 v[82:83], v[82:83], v[190:191]
	v_pk_mul_f32 v[80:81], v[80:81], v[218:219]
	s_waitcnt lgkmcnt(0)
	v_pk_mul_f32 v[94:95], v[94:95], v[180:181]
	v_pk_mul_f32 v[92:93], v[92:93], v[178:179]
	v_pk_fma_f32 v[68:69], v[208:209], s[30:31], v[68:69] op_sel_hi:[1,0,1]
	v_pk_fma_f32 v[72:73], v[212:213], s[30:31], v[72:73] op_sel_hi:[1,0,1]
	v_pk_fma_f32 v[78:79], v[188:189], s[30:31], v[78:79] op_sel_hi:[1,0,1]
	v_pk_fma_f32 v[76:77], v[216:217], s[30:31], v[76:77] op_sel_hi:[1,0,1]
	v_pk_fma_f32 v[82:83], v[192:193], s[30:31], v[82:83] op_sel_hi:[1,0,1]
	v_pk_fma_f32 v[80:81], v[220:221], s[30:31], v[80:81] op_sel_hi:[1,0,1]
	v_pk_fma_f32 v[94:95], v[184:185], s[30:31], v[94:95] op_sel_hi:[1,0,1]
	v_pk_fma_f32 v[92:93], v[182:183], s[30:31], v[92:93] op_sel_hi:[1,0,1]

.LBB0_1226:
	v_add_co_u32_e32 v96, vcc, 0x4400000, v136
	s_lshr_b32 s6, s22, 12
	s_nop 0
	v_addc_co_u32_e32 v97, vcc, 0, v137, vcc
	v_add_co_u32_e32 v98, vcc, 0xf7800000, v136
	s_mulk_i32 s6, 0x6000
	s_nop 0
	v_addc_co_u32_e32 v99, vcc, -1, v137, vcc
	global_load_dwordx2 v[170:171], v[98:99], off nt
	v_add_co_u32_e32 v98, vcc, 0xf7801000, v136
	v_add_u32_e32 v191, s6, v187
	s_nop 0
	v_addc_co_u32_e32 v99, vcc, -1, v137, vcc
	global_load_dwordx2 v[172:173], v[96:97], off nt
	global_load_dwordx2 v[166:167], v[96:97], off offset:512 nt
	global_load_dwordx2 v[162:163], v[96:97], off offset:1024 nt
	global_load_dwordx2 v[160:161], v[96:97], off offset:1536 nt
	global_load_dwordx2 v[168:169], v[98:99], off offset:-3584 nt
	global_load_dwordx2 v[164:165], v[98:99], off offset:-3072 nt
	global_load_dwordx2 v[158:159], v[98:99], off offset:-2560 nt
	global_load_dwordx2 v[154:155], v[98:99], off offset:-2048 nt
	global_load_dwordx2 v[156:157], v[96:97], off offset:2048 nt
	global_load_dwordx2 v[150:151], v[96:97], off offset:2560 nt
	global_load_dwordx2 v[146:147], v[96:97], off offset:3072 nt
	global_load_dwordx2 v[142:143], v[96:97], off offset:3584 nt
	global_load_dwordx2 v[152:153], v[98:99], off offset:-1536 nt
	global_load_dwordx2 v[148:149], v[98:99], off offset:-1024 nt
	global_load_dwordx2 v[140:141], v[98:99], off offset:-512 nt
	ds_read_b128 v[124:127], v191 offset:16384
	ds_read_b128 v[120:123], v191 offset:17408
	ds_read_b128 v[116:119], v191 offset:18432
	ds_read_b128 v[112:115], v191 offset:19456
	ds_read_b128 v[108:111], v191 offset:20480
	ds_read_b128 v[104:107], v191 offset:21504
	ds_read_b128 v[100:103], v191 offset:22528
	ds_read_b128 v[96:99], v191 offset:23552
	s_add_i32 s16, s88, s22
	s_cmpk_lt_i32 s16, 0x4000
	s_cselect_b64 s[18:19], -1, 0
	s_cmpk_gt_i32 s16, 0x3fff
	s_cbranch_scc1 .LBB0_1228
	s_ashr_i32 s17, s16, 31
	s_lshl_b64 s[8:9], s[16:17], 12
	v_lshl_add_u64 v[68:69], v[130:131], 0, s[8:9]
	v_lshl_add_u64 v[70:71], v[132:133], 0, s[8:9]
	global_load_dwordx2 v[64:65], v[68:69], off nt
	global_load_dwordx2 v[66:67], v[70:71], off nt
	global_load_dwordx2 v[72:73], v[68:69], off offset:512 nt
	global_load_dwordx2 v[74:75], v[70:71], off offset:512 nt
	global_load_dwordx2 v[76:77], v[68:69], off offset:1024 nt
	global_load_dwordx2 v[78:79], v[70:71], off offset:1024 nt
	global_load_dwordx2 v[80:81], v[68:69], off offset:1536 nt
	global_load_dwordx2 v[82:83], v[70:71], off offset:1536 nt
	global_load_dwordx2 v[84:85], v[68:69], off offset:2048 nt
	global_load_dwordx2 v[86:87], v[70:71], off offset:2048 nt
	global_load_dwordx2 v[88:89], v[68:69], off offset:2560 nt
	global_load_dwordx2 v[90:91], v[70:71], off offset:2560 nt
	s_lshr_b32 s6, s16, 12
	s_mulk_i32 s6, 0x6000
	v_add_u32_e32 v192, s6, v187
	ds_read_b128 v[174:177], v192 offset:16384
	ds_read_b128 v[178:181], v192 offset:17408
	global_load_dwordx2 v[210:211], v[68:69], off offset:3072 nt
	ds_read_b128 v[194:197], v192 offset:18432
	ds_read_b128 v[198:201], v192 offset:19456
	global_load_dwordx2 v[212:213], v[70:71], off offset:3072 nt
	ds_read_b128 v[202:205], v192 offset:20480
	ds_read_b128 v[206:209], v192 offset:21504
	global_load_dwordx2 v[92:93], v[68:69], off offset:3584 nt
	global_load_dwordx2 v[94:95], v[70:71], off offset:3584 nt
	s_mov_b32 s4, 0x3fb504f3
	s_waitcnt vmcnt(14)
	v_cvt_f32_f16_e32 v214, v66
	v_cvt_f32_f16_sdwa v215, v66 dst_sel:DWORD dst_unused:UNUSED_PAD src0_sel:WORD_1
	v_cvt_f32_f16_e32 v66, v67
	v_cvt_f32_f16_sdwa v67, v67 dst_sel:DWORD dst_unused:UNUSED_PAD src0_sel:WORD_1
	s_waitcnt vmcnt(12)
	v_cvt_f32_f16_e32 v216, v74
	v_cvt_f32_f16_sdwa v217, v74 dst_sel:DWORD dst_unused:UNUSED_PAD src0_sel:WORD_1
	v_cvt_f32_f16_e32 v74, v75
	v_cvt_f32_f16_sdwa v75, v75 dst_sel:DWORD dst_unused:UNUSED_PAD src0_sel:WORD_1
	s_waitcnt vmcnt(10)
	v_cvt_f32_f16_e32 v220, v78
	v_cvt_f32_f16_sdwa v221, v78 dst_sel:DWORD dst_unused:UNUSED_PAD src0_sel:WORD_1
	v_cvt_f32_f16_e32 v78, v79
	v_cvt_f32_f16_sdwa v79, v79 dst_sel:DWORD dst_unused:UNUSED_PAD src0_sel:WORD_1
	s_waitcnt vmcnt(8)
	v_cvt_f32_f16_e32 v224, v82
	v_cvt_f32_f16_sdwa v225, v82 dst_sel:DWORD dst_unused:UNUSED_PAD src0_sel:WORD_1
	v_cvt_f32_f16_e32 v82, v83
	v_cvt_f32_f16_sdwa v83, v83 dst_sel:DWORD dst_unused:UNUSED_PAD src0_sel:WORD_1
	s_waitcnt vmcnt(6)
	v_cvt_f32_f16_e32 v232, v86
	v_cvt_f32_f16_sdwa v233, v86 dst_sel:DWORD dst_unused:UNUSED_PAD src0_sel:WORD_1
	v_cvt_f32_f16_e32 v86, v87
	v_cvt_f32_f16_sdwa v87, v87 dst_sel:DWORD dst_unused:UNUSED_PAD src0_sel:WORD_1
	v_lshlrev_b32_e32 v68, 16, v64
	v_and_b32_e32 v69, 0xffff0000, v64
	v_lshlrev_b32_e32 v64, 16, v65
	v_and_b32_e32 v65, 0xffff0000, v65
	v_lshlrev_b32_e32 v70, 16, v72
	v_and_b32_e32 v71, 0xffff0000, v72
	v_lshlrev_b32_e32 v72, 16, v73
	v_and_b32_e32 v73, 0xffff0000, v73
	v_lshlrev_b32_e32 v218, 16, v76
	v_and_b32_e32 v219, 0xffff0000, v76
	v_lshlrev_b32_e32 v76, 16, v77
	v_and_b32_e32 v77, 0xffff0000, v77
	v_lshlrev_b32_e32 v222, 16, v80
	v_and_b32_e32 v223, 0xffff0000, v80
	v_lshlrev_b32_e32 v80, 16, v81
	v_and_b32_e32 v81, 0xffff0000, v81
	v_lshlrev_b32_e32 v226, 16, v84
	v_and_b32_e32 v227, 0xffff0000, v84
	v_lshlrev_b32_e32 v84, 16, v85
	v_and_b32_e32 v85, 0xffff0000, v85
	s_waitcnt lgkmcnt(5)
	v_pk_mul_f32 v[64:65], v[176:177], v[64:65]
	s_waitcnt lgkmcnt(4)
	v_pk_mul_f32 v[72:73], v[180:181], v[72:73]
	s_waitcnt lgkmcnt(3)
	v_pk_mul_f32 v[76:77], v[196:197], v[76:77]
	s_waitcnt lgkmcnt(2)
	v_pk_mul_f32 v[80:81], v[200:201], v[80:81]
	s_waitcnt lgkmcnt(1)
	v_pk_mul_f32 v[84:85], v[204:205], v[84:85]
	v_pk_mul_f32 v[68:69], v[174:175], v[68:69]
	v_pk_mul_f32 v[174:175], v[178:179], v[70:71]
	v_pk_fma_f32 v[70:71], v[66:67], s[4:5], v[64:65] op_sel_hi:[1,0,1]
	v_pk_fma_f32 v[66:67], v[74:75], s[4:5], v[72:73] op_sel_hi:[1,0,1]
	v_pk_fma_f32 v[74:75], v[78:79], s[4:5], v[76:77] op_sel_hi:[1,0,1]
	v_pk_fma_f32 v[78:79], v[82:83], s[4:5], v[80:81] op_sel_hi:[1,0,1]
	v_pk_fma_f32 v[82:83], v[86:87], s[4:5], v[84:85] op_sel_hi:[1,0,1]
	s_waitcnt vmcnt(5)
	v_lshlrev_b32_e32 v84, 16, v88
	v_and_b32_e32 v85, 0xffff0000, v88
	v_lshlrev_b32_e32 v86, 16, v89
	v_and_b32_e32 v87, 0xffff0000, v89
	s_waitcnt vmcnt(4)
	v_cvt_f32_f16_e32 v88, v90
	v_cvt_f32_f16_sdwa v89, v90 dst_sel:DWORD dst_unused:UNUSED_PAD src0_sel:WORD_1
	s_waitcnt lgkmcnt(0)
	v_pk_mul_f32 v[84:85], v[206:207], v[84:85]
	v_pk_fma_f32 v[64:65], v[216:217], s[4:5], v[174:175] op_sel_hi:[1,0,1]
	v_cvt_f32_f16_e32 v174, v91
	v_cvt_f32_f16_sdwa v175, v91 dst_sel:DWORD dst_unused:UNUSED_PAD src0_sel:WORD_1
	v_pk_fma_f32 v[84:85], v[88:89], s[4:5], v[84:85] op_sel_hi:[1,0,1]
	ds_read_b128 v[88:91], v192 offset:22528
	v_pk_mul_f32 v[176:177], v[194:195], v[218:219]
	v_pk_mul_f32 v[86:87], v[208:209], v[86:87]
	v_pk_fma_f32 v[72:73], v[220:221], s[4:5], v[176:177] op_sel_hi:[1,0,1]
	s_waitcnt vmcnt(2)
	v_cvt_f32_f16_e32 v176, v212
	v_cvt_f32_f16_sdwa v177, v212 dst_sel:DWORD dst_unused:UNUSED_PAD src0_sel:WORD_1
	v_pk_mul_f32 v[178:179], v[198:199], v[222:223]
	v_pk_fma_f32 v[86:87], v[174:175], s[4:5], v[86:87] op_sel_hi:[1,0,1]
	v_lshlrev_b32_e32 v174, 16, v210
	v_and_b32_e32 v175, 0xffff0000, v210
	ds_read_b128 v[192:195], v192 offset:23552
	v_pk_mul_f32 v[180:181], v[202:203], v[226:227]
	v_pk_fma_f32 v[76:77], v[224:225], s[4:5], v[178:179] op_sel_hi:[1,0,1]
	v_lshlrev_b32_e32 v178, 16, v211
	v_and_b32_e32 v179, 0xffff0000, v211
	s_waitcnt lgkmcnt(1)
	v_pk_mul_f32 v[88:89], v[88:89], v[174:175]
	v_pk_fma_f32 v[80:81], v[232:233], s[4:5], v[180:181] op_sel_hi:[1,0,1]
	v_cvt_f32_f16_e32 v180, v213
	v_cvt_f32_f16_sdwa v181, v213 dst_sel:DWORD dst_unused:UNUSED_PAD src0_sel:WORD_1
	v_pk_mul_f32 v[90:91], v[90:91], v[178:179]
	v_pk_fma_f32 v[88:89], v[176:177], s[4:5], v[88:89] op_sel_hi:[1,0,1]
	s_waitcnt vmcnt(0)
	v_cvt_f32_f16_e32 v176, v94
	v_cvt_f32_f16_e32 v178, v95
	v_cvt_f32_f16_sdwa v179, v95 dst_sel:DWORD dst_unused:UNUSED_PAD src0_sel:WORD_1
	v_cvt_f32_f16_sdwa v177, v94 dst_sel:DWORD dst_unused:UNUSED_PAD src0_sel:WORD_1
	v_lshlrev_b32_e32 v174, 16, v92
	v_and_b32_e32 v175, 0xffff0000, v92
	v_lshlrev_b32_e32 v92, 16, v93
	v_and_b32_e32 v93, 0xffff0000, v93
	s_waitcnt lgkmcnt(0)
	v_pk_mul_f32 v[92:93], v[194:195], v[92:93]
	v_pk_mul_f32 v[174:175], v[192:193], v[174:175]
	v_pk_fma_f32 v[68:69], v[214:215], s[4:5], v[68:69] op_sel_hi:[1,0,1]
	v_pk_fma_f32 v[90:91], v[180:181], s[4:5], v[90:91] op_sel_hi:[1,0,1]
	v_pk_fma_f32 v[94:95], v[178:179], s[4:5], v[92:93] op_sel_hi:[1,0,1]
	v_pk_fma_f32 v[92:93], v[176:177], s[4:5], v[174:175] op_sel_hi:[1,0,1]
